# z-GEMM+SiLU-gate epilogue: the 15 in-place loads of o issued up front into dead MFMA-operand registers (were load/wait/compute/store one at a time)
# speedup vs baseline: 1.0169x; 1.0114x over previous
; DI unsigned cvt_pk_bf16(float lo, float hi) { const f32x2_t v = {lo, hi}; const bf16v2_t b = __builtin_convertvector(v, bf16v2_t); return __builtin_bit_cast(unsigned, b); }
;     DI void operator()(const f32x4 (&acc)[2][2][4][2], const Unit& u, int wr, int wc, int fr, int fq) const {
;         const int row0 = u.pm * BM + wr * 64 + fr, col0 = u.pn * BM + wc * 32 + 8 * fq;
; #pragma unroll
;         for (int ai = 0; ai < 2; ++ai)
; #pragma unroll
;             for (int m = 0; m < 4; ++m)
; #pragma unroll
;                 for (int bj = 0; bj < 2; ++bj) f.store8(row0 + ai * HALF + m * 16, col0 + bj * HALF, acc[ai][bj][m][0], acc[ai][bj][m][1]);
;     DI void store8(int row, int col, f32x4 a, f32x4 b) const {
;         bf16_t* d = o + (size_t)row * 2048 + col;
;         const u32x4 ov = *(const u32x4*)d;
;         const unsigned ow[4] = {ov.x, ov.y, ov.z, ov.w}; float y[8];
; #pragma unroll
;         for (int i = 0; i < 8; ++i) { const float z = i < 4 ? a[i] : b[i - 4]; const float of = (i & 1) ? __uint_as_float(ow[i >> 1] & 0xffff0000u) : __uint_as_float(ow[i >> 1] << 16); y[i] = z * __builtin_amdgcn_rcpf(1.f + __expf(-z)) * of; }
;         u32x4 w; w.x = cvt_pk_bf16(y[0], y[1]); w.y = cvt_pk_bf16(y[2], y[3]); w.z = cvt_pk_bf16(y[4], y[5]); w.w = cvt_pk_bf16(y[6], y[7]); if (!dry) *(u32x4*)d = w;
.LBB0_61:
	v_lshl_add_u32 v142, s20, 8, v146
	v_ashrrev_i32_e32 v143, 31, v142
	v_lshl_or_b32 v144, s21, 8, v148
	v_lshlrev_b64 v[140:141], 12, v[142:143]
	v_ashrrev_i32_e32 v145, 31, v144
	v_lshl_add_u64 v[140:141], s[0:1], 0, v[140:141]
	v_lshlrev_b64 v[144:145], 1, v[144:145]
	v_lshl_add_u64 v[140:141], v[140:141], 0, v[144:145]
	global_load_dwordx4 v[150:153], v[140:141], off
	global_load_dwordx4 v[176:179], v[140:141], off offset:256
	v_add_co_u32_e32 v162, vcc, 0x10000, v140
	s_nop 1
	v_addc_co_u32_e32 v163, vcc, 0, v141, vcc
	global_load_dwordx4 v[180:183], v[162:163], off
	global_load_dwordx4 v[190:193], v[162:163], off offset:256
	v_add_co_u32_e32 v162, vcc, 0x20000, v140
	s_nop 1
	v_addc_co_u32_e32 v163, vcc, 0, v141, vcc
	global_load_dwordx4 v[194:197], v[162:163], off
	global_load_dwordx4 v[198:201], v[162:163], off offset:256
	v_add_co_u32_e32 v162, vcc, 0x30000, v140
	s_nop 1
	v_addc_co_u32_e32 v163, vcc, 0, v141, vcc
	global_load_dwordx4 v[202:205], v[162:163], off
	global_load_dwordx4 v[206:209], v[162:163], off offset:256
	v_add_co_u32_e32 v162, vcc, 0x80000, v140
	s_nop 1
	v_addc_co_u32_e32 v163, vcc, 0, v141, vcc
	global_load_dwordx4 v[210:213], v[162:163], off
	global_load_dwordx4 v[214:217], v[162:163], off offset:256
	v_add_co_u32_e32 v162, vcc, 0x90000, v140
	s_nop 1
	v_addc_co_u32_e32 v163, vcc, 0, v141, vcc
	global_load_dwordx4 v[218:221], v[162:163], off
	global_load_dwordx4 v[222:225], v[162:163], off offset:256
	v_add_co_u32_e32 v162, vcc, 0xa0000, v140
	s_nop 1
	v_addc_co_u32_e32 v163, vcc, 0, v141, vcc
	global_load_dwordx4 v[226:229], v[162:163], off
	global_load_dwordx4 v[248:251], v[162:163], off offset:256
	v_add_co_u32_e32 v162, vcc, 0xb0000, v140
	s_nop 1
	v_addc_co_u32_e32 v163, vcc, 0, v141, vcc
	global_load_dwordx4 v[252:255], v[162:163], off
	v_mul_f32_e32 v143, 0xbfb8aa3b, v124
	v_exp_f32_e32 v143, v143
	s_mov_b32 s13, 0x80000
	s_mov_b64 s[20:21], 0x80000
	v_add_f32_e32 v143, 1.0, v143
	v_rcp_f32_e32 v154, v143
	v_mul_f32_e32 v143, 0xbfb8aa3b, v122
	v_exp_f32_e32 v143, v143
	s_nop 0
	v_add_f32_e32 v143, 1.0, v143
	v_rcp_f32_e32 v156, v143
	v_mul_f32_e32 v143, 0xbfb8aa3b, v123
	v_exp_f32_e32 v143, v143
	s_nop 0
	v_add_f32_e32 v143, 1.0, v143
	v_rcp_f32_e32 v157, v143
	s_nop 0
	v_pk_mul_f32 v[122:123], v[122:123], v[156:157]
	s_waitcnt vmcnt(14)
	v_lshlrev_b32_e32 v156, 16, v152
	v_and_b32_e32 v157, 0xffff0000, v152
	v_pk_mul_f32 v[156:157], v[122:123], v[156:157]
	v_mul_f32_e32 v122, 0xbfb8aa3b, v128
	v_mul_f32_e32 v123, 0xbfb8aa3b, v129
	v_exp_f32_e32 v122, v122
	v_exp_f32_e32 v123, v123
	v_add_f32_e32 v122, 1.0, v122
	v_add_f32_e32 v123, 1.0, v123
	v_rcp_f32_e32 v122, v122
	v_rcp_f32_e32 v123, v123
	s_nop 0
	v_pk_mul_f32 v[122:123], v[128:129], v[122:123]
	v_lshlrev_b32_e32 v128, 16, v151
	v_and_b32_e32 v129, 0xffff0000, v151
	v_pk_mul_f32 v[128:129], v[122:123], v[128:129]
	v_mul_f32_e32 v122, 0xbfb8aa3b, v126
	v_mul_f32_e32 v123, 0xbfb8aa3b, v127
	v_exp_f32_e32 v122, v122
	v_exp_f32_e32 v123, v123
	v_add_f32_e32 v122, 1.0, v122
	v_add_f32_e32 v123, 1.0, v123
	v_rcp_f32_e32 v122, v122
	v_rcp_f32_e32 v123, v123
	s_nop 0
	v_pk_mul_f32 v[122:123], v[126:127], v[122:123]
	v_lshlrev_b32_e32 v126, 16, v150
	v_and_b32_e32 v127, 0xffff0000, v150
	v_pk_mul_f32 v[122:123], v[122:123], v[126:127]
	v_mul_f32_e32 v126, 0xbfb8aa3b, v125
	v_exp_f32_e32 v126, v126
	v_and_b32_e32 v127, 0xffff0000, v153
	v_cvt_pk_bf16_f32 v122, v122, v123
	v_cvt_pk_bf16_f32 v123, v128, v129
	v_add_f32_e32 v126, 1.0, v126
	v_rcp_f32_e32 v155, v126
	v_lshlrev_b32_e32 v126, 16, v153
	v_pk_mul_f32 v[124:125], v[124:125], v[154:155]
	s_nop 0
	v_pk_mul_f32 v[126:127], v[124:125], v[126:127]
	v_cvt_pk_bf16_f32 v124, v156, v157
	v_cvt_pk_bf16_f32 v125, v126, v127
	global_store_dwordx4 v[140:141], v[122:125], off
	s_nop 0
	s_nop 0
	v_mul_f32_e32 v123, 0xbfb8aa3b, v114
	v_exp_f32_e32 v123, v123
	v_mul_f32_e32 v122, 0xbfb8aa3b, v116
	v_exp_f32_e32 v122, v122
	v_add_f32_e32 v123, 1.0, v123
	v_rcp_f32_e32 v128, v123
	v_mul_f32_e32 v123, 0xbfb8aa3b, v115
	v_exp_f32_e32 v123, v123
	v_add_f32_e32 v122, 1.0, v122
	v_rcp_f32_e32 v122, v122
	v_add_f32_e32 v123, 1.0, v123
	v_rcp_f32_e32 v129, v123
	s_nop 0
	v_pk_mul_f32 v[114:115], v[114:115], v[128:129]
	s_waitcnt vmcnt(0)
; DI unsigned cvt_pk_bf16(float lo, float hi) { const f32x2_t v = {lo, hi}; const bf16v2_t b = __builtin_convertvector(v, bf16v2_t); return __builtin_bit_cast(unsigned, b); }
;     DI void operator()(const f32x4 (&acc)[2][2][4][2], const Unit& u, int wr, int wc, int fr, int fq) const {
;         const int row0 = u.pm * BM + wr * 64 + fr, col0 = u.pn * BM + wc * 32 + 8 * fq;
; #pragma unroll
;         for (int ai = 0; ai < 2; ++ai)
; #pragma unroll
;             for (int m = 0; m < 4; ++m)
; #pragma unroll
;                 for (int bj = 0; bj < 2; ++bj) f.store8(row0 + ai * HALF + m * 16, col0 + bj * HALF, acc[ai][bj][m][0], acc[ai][bj][m][1]);
;     DI void store8(int row, int col, f32x4 a, f32x4 b) const {
;         bf16_t* d = o + (size_t)row * 2048 + col;
;         const u32x4 ov = *(const u32x4*)d;
;         const unsigned ow[4] = {ov.x, ov.y, ov.z, ov.w}; float y[8];
; #pragma unroll
;         for (int i = 0; i < 8; ++i) { const float z = i < 4 ? a[i] : b[i - 4]; const float of = (i & 1) ? __uint_as_float(ow[i >> 1] & 0xffff0000u) : __uint_as_float(ow[i >> 1] << 16); y[i] = z * __builtin_amdgcn_rcpf(1.f + __expf(-z)) * of; }
;         u32x4 w; w.x = cvt_pk_bf16(y[0], y[1]); w.y = cvt_pk_bf16(y[2], y[3]); w.z = cvt_pk_bf16(y[4], y[5]); w.w = cvt_pk_bf16(y[6], y[7]); if (!dry) *(u32x4*)d = w;
	v_lshlrev_b32_e32 v128, 16, v178
	v_and_b32_e32 v129, 0xffff0000, v178
	v_pk_mul_f32 v[128:129], v[114:115], v[128:129]
	v_mul_f32_e32 v114, 0xbfb8aa3b, v120
	v_mul_f32_e32 v115, 0xbfb8aa3b, v121
	v_exp_f32_e32 v114, v114
	v_exp_f32_e32 v115, v115
	v_add_f32_e32 v114, 1.0, v114
	v_add_f32_e32 v115, 1.0, v115
	v_rcp_f32_e32 v114, v114
	v_rcp_f32_e32 v115, v115
	s_nop 0
	v_pk_mul_f32 v[114:115], v[120:121], v[114:115]
	v_lshlrev_b32_e32 v120, 16, v177
	v_and_b32_e32 v121, 0xffff0000, v177
	v_pk_mul_f32 v[120:121], v[114:115], v[120:121]
	v_mul_f32_e32 v114, 0xbfb8aa3b, v118
	v_mul_f32_e32 v115, 0xbfb8aa3b, v119
	v_exp_f32_e32 v114, v114
	v_exp_f32_e32 v115, v115
	v_add_f32_e32 v114, 1.0, v114
	v_add_f32_e32 v115, 1.0, v115
	v_rcp_f32_e32 v114, v114
	v_rcp_f32_e32 v115, v115
	s_nop 0
	v_pk_mul_f32 v[114:115], v[118:119], v[114:115]
	v_lshlrev_b32_e32 v118, 16, v176
	v_and_b32_e32 v119, 0xffff0000, v176
	v_pk_mul_f32 v[114:115], v[114:115], v[118:119]
	v_mul_f32_e32 v118, 0xbfb8aa3b, v117
	v_exp_f32_e32 v118, v118
	v_and_b32_e32 v119, 0xffff0000, v179
	v_cvt_pk_bf16_f32 v114, v114, v115
	v_cvt_pk_bf16_f32 v115, v120, v121
	v_add_f32_e32 v118, 1.0, v118
	v_rcp_f32_e32 v123, v118
	v_lshlrev_b32_e32 v118, 16, v179
	v_mul_f32_e32 v121, 0xbfb8aa3b, v106
	v_exp_f32_e32 v121, v121
	v_pk_mul_f32 v[116:117], v[116:117], v[122:123]
	v_add_f32_e32 v121, 1.0, v121
	v_pk_mul_f32 v[118:119], v[116:117], v[118:119]
	v_cvt_pk_bf16_f32 v116, v128, v129
	v_cvt_pk_bf16_f32 v117, v118, v119
	global_store_dwordx4 v[140:141], v[114:117], off offset:256
	v_rcp_f32_e32 v122, v121
	v_mul_f32_e32 v121, 0xbfb8aa3b, v107
	v_mul_f32_e32 v116, 0xbfb8aa3b, v108
	v_or_b32_e32 v114, 16, v142
	v_exp_f32_e32 v116, v116
	v_ashrrev_i32_e32 v115, 31, v114
	v_lshlrev_b64 v[114:115], 12, v[114:115]
	v_lshl_add_u64 v[114:115], s[0:1], 0, v[114:115]
	v_add_f32_e32 v116, 1.0, v116
	v_lshl_add_u64 v[114:115], v[114:115], 0, v[144:145]
	v_rcp_f32_e32 v120, v116
	s_nop 0
	v_exp_f32_e32 v121, v121
	s_nop 0
	v_add_f32_e32 v121, 1.0, v121
	v_rcp_f32_e32 v123, v121
	s_nop 0
	v_pk_mul_f32 v[106:107], v[106:107], v[122:123]
	v_lshlrev_b32_e32 v122, 16, v182
	v_and_b32_e32 v123, 0xffff0000, v182
	v_pk_mul_f32 v[122:123], v[106:107], v[122:123]
	v_mul_f32_e32 v106, 0xbfb8aa3b, v112
	v_mul_f32_e32 v107, 0xbfb8aa3b, v113
	v_exp_f32_e32 v106, v106
	v_exp_f32_e32 v107, v107
	v_add_f32_e32 v106, 1.0, v106
	v_add_f32_e32 v107, 1.0, v107
	v_rcp_f32_e32 v106, v106
	v_rcp_f32_e32 v107, v107
	s_nop 0
	v_pk_mul_f32 v[106:107], v[112:113], v[106:107]
	v_lshlrev_b32_e32 v112, 16, v181
	v_and_b32_e32 v113, 0xffff0000, v181
	v_pk_mul_f32 v[112:113], v[106:107], v[112:113]
	v_mul_f32_e32 v106, 0xbfb8aa3b, v110
	v_mul_f32_e32 v107, 0xbfb8aa3b, v111
	v_exp_f32_e32 v106, v106
	v_exp_f32_e32 v107, v107
	v_add_f32_e32 v106, 1.0, v106
	v_add_f32_e32 v107, 1.0, v107
	v_rcp_f32_e32 v106, v106
	v_rcp_f32_e32 v107, v107
	s_nop 0
	v_pk_mul_f32 v[106:107], v[110:111], v[106:107]
	v_lshlrev_b32_e32 v110, 16, v180
	v_and_b32_e32 v111, 0xffff0000, v180
	v_pk_mul_f32 v[106:107], v[106:107], v[110:111]
	v_mul_f32_e32 v110, 0xbfb8aa3b, v109
	v_exp_f32_e32 v110, v110
	v_and_b32_e32 v111, 0xffff0000, v183
	v_cvt_pk_bf16_f32 v106, v106, v107
	v_cvt_pk_bf16_f32 v107, v112, v113
	v_add_f32_e32 v110, 1.0, v110
	v_rcp_f32_e32 v121, v110
	v_lshlrev_b32_e32 v110, 16, v183
	v_pk_mul_f32 v[108:109], v[108:109], v[120:121]
	s_nop 0
	v_pk_mul_f32 v[110:111], v[108:109], v[110:111]
	v_cvt_pk_bf16_f32 v108, v122, v123
	v_cvt_pk_bf16_f32 v109, v110, v111
	global_store_dwordx4 v[114:115], v[106:109], off
	s_nop 0
	s_nop 0
	v_mul_f32_e32 v107, 0xbfb8aa3b, v98
	v_exp_f32_e32 v107, v107
	v_mul_f32_e32 v106, 0xbfb8aa3b, v100
	v_exp_f32_e32 v106, v106
	v_add_f32_e32 v107, 1.0, v107
	v_rcp_f32_e32 v112, v107
	v_mul_f32_e32 v107, 0xbfb8aa3b, v99
	v_exp_f32_e32 v107, v107
	v_add_f32_e32 v106, 1.0, v106
	v_rcp_f32_e32 v106, v106
	v_add_f32_e32 v107, 1.0, v107
	v_rcp_f32_e32 v113, v107
	s_nop 0
	v_pk_mul_f32 v[98:99], v[98:99], v[112:113]
	v_lshlrev_b32_e32 v112, 16, v192
	v_and_b32_e32 v113, 0xffff0000, v192
	v_pk_mul_f32 v[112:113], v[98:99], v[112:113]
	v_mul_f32_e32 v98, 0xbfb8aa3b, v104
	v_mul_f32_e32 v99, 0xbfb8aa3b, v105
	v_exp_f32_e32 v98, v98
	v_exp_f32_e32 v99, v99
	v_add_f32_e32 v98, 1.0, v98
	v_add_f32_e32 v99, 1.0, v99
	v_rcp_f32_e32 v98, v98
	v_rcp_f32_e32 v99, v99
	s_nop 0
	v_pk_mul_f32 v[98:99], v[104:105], v[98:99]
	v_lshlrev_b32_e32 v104, 16, v191
	v_and_b32_e32 v105, 0xffff0000, v191
	v_pk_mul_f32 v[104:105], v[98:99], v[104:105]
	v_mul_f32_e32 v98, 0xbfb8aa3b, v102
	v_mul_f32_e32 v99, 0xbfb8aa3b, v103
	v_exp_f32_e32 v98, v98
	v_exp_f32_e32 v99, v99
	v_add_f32_e32 v98, 1.0, v98
	v_add_f32_e32 v99, 1.0, v99
	v_rcp_f32_e32 v98, v98
	v_rcp_f32_e32 v99, v99
	s_nop 0
	v_pk_mul_f32 v[98:99], v[102:103], v[98:99]
	v_lshlrev_b32_e32 v102, 16, v190
	v_and_b32_e32 v103, 0xffff0000, v190
	v_pk_mul_f32 v[98:99], v[98:99], v[102:103]
	v_mul_f32_e32 v102, 0xbfb8aa3b, v101
	v_exp_f32_e32 v102, v102
	v_and_b32_e32 v103, 0xffff0000, v193
	v_cvt_pk_bf16_f32 v98, v98, v99
	v_cvt_pk_bf16_f32 v99, v104, v105
	v_add_f32_e32 v102, 1.0, v102
	v_rcp_f32_e32 v107, v102
	v_lshlrev_b32_e32 v102, 16, v193
	v_mul_f32_e32 v105, 0xbfb8aa3b, v90
	v_exp_f32_e32 v105, v105
	v_pk_mul_f32 v[100:101], v[100:101], v[106:107]
	v_add_f32_e32 v105, 1.0, v105
	v_pk_mul_f32 v[102:103], v[100:101], v[102:103]
	v_cvt_pk_bf16_f32 v100, v112, v113
	v_cvt_pk_bf16_f32 v101, v102, v103
	global_store_dwordx4 v[114:115], v[98:101], off offset:256
	v_rcp_f32_e32 v106, v105
	v_mul_f32_e32 v105, 0xbfb8aa3b, v91
	v_mul_f32_e32 v100, 0xbfb8aa3b, v92
	v_or_b32_e32 v98, 32, v142
; DI unsigned cvt_pk_bf16(float lo, float hi) { const f32x2_t v = {lo, hi}; const bf16v2_t b = __builtin_convertvector(v, bf16v2_t); return __builtin_bit_cast(unsigned, b); }
;     DI void operator()(const f32x4 (&acc)[2][2][4][2], const Unit& u, int wr, int wc, int fr, int fq) const {
;         const int row0 = u.pm * BM + wr * 64 + fr, col0 = u.pn * BM + wc * 32 + 8 * fq;
; #pragma unroll
;         for (int ai = 0; ai < 2; ++ai)
; #pragma unroll
;             for (int m = 0; m < 4; ++m)
; #pragma unroll
;                 for (int bj = 0; bj < 2; ++bj) f.store8(row0 + ai * HALF + m * 16, col0 + bj * HALF, acc[ai][bj][m][0], acc[ai][bj][m][1]);
;     DI void store8(int row, int col, f32x4 a, f32x4 b) const {
;         bf16_t* d = o + (size_t)row * 2048 + col;
;         const u32x4 ov = *(const u32x4*)d;
;         const unsigned ow[4] = {ov.x, ov.y, ov.z, ov.w}; float y[8];
; #pragma unroll
;         for (int i = 0; i < 8; ++i) { const float z = i < 4 ? a[i] : b[i - 4]; const float of = (i & 1) ? __uint_as_float(ow[i >> 1] & 0xffff0000u) : __uint_as_float(ow[i >> 1] << 16); y[i] = z * __builtin_amdgcn_rcpf(1.f + __expf(-z)) * of; }
;         u32x4 w; w.x = cvt_pk_bf16(y[0], y[1]); w.y = cvt_pk_bf16(y[2], y[3]); w.z = cvt_pk_bf16(y[4], y[5]); w.w = cvt_pk_bf16(y[6], y[7]); if (!dry) *(u32x4*)d = w;
	v_exp_f32_e32 v100, v100
	v_ashrrev_i32_e32 v99, 31, v98
	v_lshlrev_b64 v[98:99], 12, v[98:99]
	v_lshl_add_u64 v[98:99], s[0:1], 0, v[98:99]
	v_add_f32_e32 v100, 1.0, v100
	v_lshl_add_u64 v[98:99], v[98:99], 0, v[144:145]
	v_rcp_f32_e32 v104, v100
	s_nop 0
	v_exp_f32_e32 v105, v105
	s_nop 0
	v_add_f32_e32 v105, 1.0, v105
	v_rcp_f32_e32 v107, v105
	s_nop 0
	v_pk_mul_f32 v[90:91], v[90:91], v[106:107]
	v_lshlrev_b32_e32 v106, 16, v196
	v_and_b32_e32 v107, 0xffff0000, v196
	v_pk_mul_f32 v[106:107], v[90:91], v[106:107]
	v_mul_f32_e32 v90, 0xbfb8aa3b, v96
	v_mul_f32_e32 v91, 0xbfb8aa3b, v97
	v_exp_f32_e32 v90, v90
	v_exp_f32_e32 v91, v91
	v_add_f32_e32 v90, 1.0, v90
	v_add_f32_e32 v91, 1.0, v91
	v_rcp_f32_e32 v90, v90
	v_rcp_f32_e32 v91, v91
	s_nop 0
	v_pk_mul_f32 v[90:91], v[96:97], v[90:91]
	v_lshlrev_b32_e32 v96, 16, v195
	v_and_b32_e32 v97, 0xffff0000, v195
	v_pk_mul_f32 v[96:97], v[90:91], v[96:97]
	v_mul_f32_e32 v90, 0xbfb8aa3b, v94
	v_mul_f32_e32 v91, 0xbfb8aa3b, v95
	v_exp_f32_e32 v90, v90
	v_exp_f32_e32 v91, v91
	v_add_f32_e32 v90, 1.0, v90
	v_add_f32_e32 v91, 1.0, v91
	v_rcp_f32_e32 v90, v90
	v_rcp_f32_e32 v91, v91
	s_nop 0
	v_pk_mul_f32 v[90:91], v[94:95], v[90:91]
	v_lshlrev_b32_e32 v94, 16, v194
	v_and_b32_e32 v95, 0xffff0000, v194
	v_pk_mul_f32 v[90:91], v[90:91], v[94:95]
	v_mul_f32_e32 v94, 0xbfb8aa3b, v93
	v_exp_f32_e32 v94, v94
	v_and_b32_e32 v95, 0xffff0000, v197
	v_cvt_pk_bf16_f32 v90, v90, v91
	v_cvt_pk_bf16_f32 v91, v96, v97
	v_add_f32_e32 v94, 1.0, v94
	v_rcp_f32_e32 v105, v94
	v_lshlrev_b32_e32 v94, 16, v197
	v_pk_mul_f32 v[92:93], v[92:93], v[104:105]
	s_nop 0
	v_pk_mul_f32 v[94:95], v[92:93], v[94:95]
	v_cvt_pk_bf16_f32 v92, v106, v107
	v_cvt_pk_bf16_f32 v93, v94, v95
	global_store_dwordx4 v[98:99], v[90:93], off
	s_nop 0
	s_nop 0
	v_mul_f32_e32 v91, 0xbfb8aa3b, v82
	v_exp_f32_e32 v91, v91
	v_mul_f32_e32 v90, 0xbfb8aa3b, v84
	v_exp_f32_e32 v90, v90
	v_add_f32_e32 v91, 1.0, v91
	v_rcp_f32_e32 v96, v91
	v_mul_f32_e32 v91, 0xbfb8aa3b, v83
	v_exp_f32_e32 v91, v91
	v_add_f32_e32 v90, 1.0, v90
	v_rcp_f32_e32 v90, v90
	v_add_f32_e32 v91, 1.0, v91
	v_rcp_f32_e32 v97, v91
	s_nop 0
	v_pk_mul_f32 v[82:83], v[82:83], v[96:97]
	v_lshlrev_b32_e32 v96, 16, v200
	v_and_b32_e32 v97, 0xffff0000, v200
	v_pk_mul_f32 v[96:97], v[82:83], v[96:97]
	v_mul_f32_e32 v82, 0xbfb8aa3b, v88
	v_mul_f32_e32 v83, 0xbfb8aa3b, v89
	v_exp_f32_e32 v82, v82
	v_exp_f32_e32 v83, v83
	v_add_f32_e32 v82, 1.0, v82
	v_add_f32_e32 v83, 1.0, v83
	v_rcp_f32_e32 v82, v82
	v_rcp_f32_e32 v83, v83
	s_nop 0
	v_pk_mul_f32 v[82:83], v[88:89], v[82:83]
	v_lshlrev_b32_e32 v88, 16, v199
	v_and_b32_e32 v89, 0xffff0000, v199
	v_pk_mul_f32 v[88:89], v[82:83], v[88:89]
	v_mul_f32_e32 v82, 0xbfb8aa3b, v86
	v_mul_f32_e32 v83, 0xbfb8aa3b, v87
	v_exp_f32_e32 v82, v82
	v_exp_f32_e32 v83, v83
	v_add_f32_e32 v82, 1.0, v82
	v_add_f32_e32 v83, 1.0, v83
	v_rcp_f32_e32 v82, v82
	v_rcp_f32_e32 v83, v83
	s_nop 0
	v_pk_mul_f32 v[82:83], v[86:87], v[82:83]
	v_lshlrev_b32_e32 v86, 16, v198
	v_and_b32_e32 v87, 0xffff0000, v198
	v_pk_mul_f32 v[82:83], v[82:83], v[86:87]
	v_mul_f32_e32 v86, 0xbfb8aa3b, v85
	v_exp_f32_e32 v86, v86
	v_and_b32_e32 v87, 0xffff0000, v201
	v_cvt_pk_bf16_f32 v82, v82, v83
	v_cvt_pk_bf16_f32 v83, v88, v89
	v_add_f32_e32 v86, 1.0, v86
	v_rcp_f32_e32 v91, v86
	v_lshlrev_b32_e32 v86, 16, v201
	v_mul_f32_e32 v89, 0xbfb8aa3b, v74
	v_exp_f32_e32 v89, v89
	v_pk_mul_f32 v[84:85], v[84:85], v[90:91]
	v_add_f32_e32 v89, 1.0, v89
	v_pk_mul_f32 v[86:87], v[84:85], v[86:87]
	v_cvt_pk_bf16_f32 v84, v96, v97
	v_cvt_pk_bf16_f32 v85, v86, v87
	global_store_dwordx4 v[98:99], v[82:85], off offset:256
	v_rcp_f32_e32 v90, v89
	v_mul_f32_e32 v89, 0xbfb8aa3b, v75
	v_mul_f32_e32 v84, 0xbfb8aa3b, v76
	v_or_b32_e32 v82, 48, v142
	v_exp_f32_e32 v84, v84
	v_ashrrev_i32_e32 v83, 31, v82
	v_lshlrev_b64 v[82:83], 12, v[82:83]
	v_lshl_add_u64 v[82:83], s[0:1], 0, v[82:83]
	v_add_f32_e32 v84, 1.0, v84
	v_lshl_add_u64 v[82:83], v[82:83], 0, v[144:145]
	v_rcp_f32_e32 v88, v84
	s_nop 0
	v_exp_f32_e32 v89, v89
	s_nop 0
	v_add_f32_e32 v89, 1.0, v89
	v_rcp_f32_e32 v91, v89
	s_nop 0
	v_pk_mul_f32 v[74:75], v[74:75], v[90:91]
	v_lshlrev_b32_e32 v90, 16, v204
	v_and_b32_e32 v91, 0xffff0000, v204
	v_pk_mul_f32 v[90:91], v[74:75], v[90:91]
	v_mul_f32_e32 v74, 0xbfb8aa3b, v80
	v_mul_f32_e32 v75, 0xbfb8aa3b, v81
	v_exp_f32_e32 v74, v74
	v_exp_f32_e32 v75, v75
	v_add_f32_e32 v74, 1.0, v74
	v_add_f32_e32 v75, 1.0, v75
	v_rcp_f32_e32 v74, v74
	v_rcp_f32_e32 v75, v75
	s_nop 0
	v_pk_mul_f32 v[74:75], v[80:81], v[74:75]
	v_lshlrev_b32_e32 v80, 16, v203
	v_and_b32_e32 v81, 0xffff0000, v203
	v_pk_mul_f32 v[80:81], v[74:75], v[80:81]
	v_mul_f32_e32 v74, 0xbfb8aa3b, v78
	v_mul_f32_e32 v75, 0xbfb8aa3b, v79
	v_exp_f32_e32 v74, v74
	v_exp_f32_e32 v75, v75
	v_add_f32_e32 v74, 1.0, v74
	v_add_f32_e32 v75, 1.0, v75
	v_rcp_f32_e32 v74, v74
	v_rcp_f32_e32 v75, v75
	s_nop 0
	v_pk_mul_f32 v[74:75], v[78:79], v[74:75]
	v_lshlrev_b32_e32 v78, 16, v202
	v_and_b32_e32 v79, 0xffff0000, v202
	v_pk_mul_f32 v[74:75], v[74:75], v[78:79]
	v_mul_f32_e32 v78, 0xbfb8aa3b, v77
	v_exp_f32_e32 v78, v78
	v_and_b32_e32 v79, 0xffff0000, v205
	v_cvt_pk_bf16_f32 v74, v74, v75
	v_cvt_pk_bf16_f32 v75, v80, v81
	v_add_f32_e32 v78, 1.0, v78
	v_rcp_f32_e32 v89, v78
	v_lshlrev_b32_e32 v78, 16, v205
	v_pk_mul_f32 v[76:77], v[76:77], v[88:89]
	s_nop 0
	v_pk_mul_f32 v[78:79], v[76:77], v[78:79]
	v_cvt_pk_bf16_f32 v76, v90, v91
	v_cvt_pk_bf16_f32 v77, v78, v79
	global_store_dwordx4 v[82:83], v[74:77], off
	s_nop 0
	s_nop 0
	v_mul_f32_e32 v75, 0xbfb8aa3b, v66
	v_exp_f32_e32 v75, v75
	v_mul_f32_e32 v74, 0xbfb8aa3b, v68
	v_exp_f32_e32 v74, v74
	v_add_f32_e32 v75, 1.0, v75
; DI unsigned cvt_pk_bf16(float lo, float hi) { const f32x2_t v = {lo, hi}; const bf16v2_t b = __builtin_convertvector(v, bf16v2_t); return __builtin_bit_cast(unsigned, b); }
;     DI void operator()(const f32x4 (&acc)[2][2][4][2], const Unit& u, int wr, int wc, int fr, int fq) const {
;         const int row0 = u.pm * BM + wr * 64 + fr, col0 = u.pn * BM + wc * 32 + 8 * fq;
; #pragma unroll
;         for (int ai = 0; ai < 2; ++ai)
; #pragma unroll
;             for (int m = 0; m < 4; ++m)
; #pragma unroll
;                 for (int bj = 0; bj < 2; ++bj) f.store8(row0 + ai * HALF + m * 16, col0 + bj * HALF, acc[ai][bj][m][0], acc[ai][bj][m][1]);
;     DI void store8(int row, int col, f32x4 a, f32x4 b) const {
;         bf16_t* d = o + (size_t)row * 2048 + col;
;         const u32x4 ov = *(const u32x4*)d;
;         const unsigned ow[4] = {ov.x, ov.y, ov.z, ov.w}; float y[8];
; #pragma unroll
;         for (int i = 0; i < 8; ++i) { const float z = i < 4 ? a[i] : b[i - 4]; const float of = (i & 1) ? __uint_as_float(ow[i >> 1] & 0xffff0000u) : __uint_as_float(ow[i >> 1] << 16); y[i] = z * __builtin_amdgcn_rcpf(1.f + __expf(-z)) * of; }
;         u32x4 w; w.x = cvt_pk_bf16(y[0], y[1]); w.y = cvt_pk_bf16(y[2], y[3]); w.z = cvt_pk_bf16(y[4], y[5]); w.w = cvt_pk_bf16(y[6], y[7]); if (!dry) *(u32x4*)d = w;
	v_rcp_f32_e32 v80, v75
	v_mul_f32_e32 v75, 0xbfb8aa3b, v67
	v_exp_f32_e32 v75, v75
	v_add_f32_e32 v74, 1.0, v74
	v_rcp_f32_e32 v74, v74
	v_add_f32_e32 v75, 1.0, v75
	v_rcp_f32_e32 v81, v75
	s_nop 0
	v_pk_mul_f32 v[66:67], v[66:67], v[80:81]
	v_lshlrev_b32_e32 v80, 16, v208
	v_and_b32_e32 v81, 0xffff0000, v208
	v_pk_mul_f32 v[80:81], v[66:67], v[80:81]
	v_mul_f32_e32 v66, 0xbfb8aa3b, v72
	v_mul_f32_e32 v67, 0xbfb8aa3b, v73
	v_exp_f32_e32 v66, v66
	v_exp_f32_e32 v67, v67
	v_add_f32_e32 v66, 1.0, v66
	v_add_f32_e32 v67, 1.0, v67
	v_rcp_f32_e32 v66, v66
	v_rcp_f32_e32 v67, v67
	s_nop 0
	v_pk_mul_f32 v[66:67], v[72:73], v[66:67]
	v_lshlrev_b32_e32 v72, 16, v207
	v_and_b32_e32 v73, 0xffff0000, v207
	v_pk_mul_f32 v[72:73], v[66:67], v[72:73]
	v_mul_f32_e32 v66, 0xbfb8aa3b, v70
	v_mul_f32_e32 v67, 0xbfb8aa3b, v71
	v_exp_f32_e32 v66, v66
	v_exp_f32_e32 v67, v67
	v_add_f32_e32 v66, 1.0, v66
	v_add_f32_e32 v67, 1.0, v67
	v_rcp_f32_e32 v66, v66
	v_rcp_f32_e32 v67, v67
	s_nop 0
	v_pk_mul_f32 v[66:67], v[70:71], v[66:67]
	v_lshlrev_b32_e32 v70, 16, v206
	v_and_b32_e32 v71, 0xffff0000, v206
	v_pk_mul_f32 v[66:67], v[66:67], v[70:71]
	v_mul_f32_e32 v70, 0xbfb8aa3b, v69
	v_exp_f32_e32 v70, v70
	v_and_b32_e32 v71, 0xffff0000, v209
	v_cvt_pk_bf16_f32 v66, v66, v67
	v_cvt_pk_bf16_f32 v67, v72, v73
	v_add_f32_e32 v70, 1.0, v70
	v_rcp_f32_e32 v75, v70
	v_lshlrev_b32_e32 v70, 16, v209
	v_pk_mul_f32 v[68:69], v[68:69], v[74:75]
	v_add_co_u32_e32 v74, vcc, s13, v140
	v_pk_mul_f32 v[70:71], v[68:69], v[70:71]
	s_nop 0
	v_addc_co_u32_e32 v75, vcc, 0, v141, vcc
	v_cvt_pk_bf16_f32 v69, v70, v71
	s_nop 0
	v_cvt_pk_bf16_f32 v68, v80, v81
	global_store_dwordx4 v[82:83], v[66:69], off offset:256
	s_mov_b32 s13, 0x90000
	s_nop 0
	v_mul_f32_e32 v69, 0xbfb8aa3b, v58
	v_exp_f32_e32 v69, v69
	v_mul_f32_e32 v66, 0xbfb8aa3b, v60
	v_exp_f32_e32 v66, v66
	v_add_f32_e32 v69, 1.0, v69
	v_rcp_f32_e32 v76, v69
	v_mul_f32_e32 v69, 0xbfb8aa3b, v59
	v_exp_f32_e32 v69, v69
	v_add_f32_e32 v66, 1.0, v66
	v_rcp_f32_e32 v68, v66
	v_lshl_add_u64 v[66:67], v[140:141], 0, s[20:21]
	v_add_f32_e32 v69, 1.0, v69
	v_rcp_f32_e32 v77, v69
	s_mov_b64 s[20:21], 0x90000
	v_pk_mul_f32 v[58:59], v[58:59], v[76:77]
	v_lshlrev_b32_e32 v76, 16, v212
	v_and_b32_e32 v77, 0xffff0000, v212
	v_pk_mul_f32 v[76:77], v[58:59], v[76:77]
	v_mul_f32_e32 v58, 0xbfb8aa3b, v64
	v_mul_f32_e32 v59, 0xbfb8aa3b, v65
	v_exp_f32_e32 v58, v58
	v_exp_f32_e32 v59, v59
	v_add_f32_e32 v58, 1.0, v58
	v_add_f32_e32 v59, 1.0, v59
	v_rcp_f32_e32 v58, v58
	v_rcp_f32_e32 v59, v59
	s_nop 0
	v_pk_mul_f32 v[58:59], v[64:65], v[58:59]
	v_lshlrev_b32_e32 v64, 16, v211
	v_and_b32_e32 v65, 0xffff0000, v211
	v_pk_mul_f32 v[64:65], v[58:59], v[64:65]
	v_mul_f32_e32 v58, 0xbfb8aa3b, v62
	v_mul_f32_e32 v59, 0xbfb8aa3b, v63
	v_exp_f32_e32 v58, v58
	v_exp_f32_e32 v59, v59
	v_add_f32_e32 v58, 1.0, v58
	v_add_f32_e32 v59, 1.0, v59
	v_rcp_f32_e32 v58, v58
	v_rcp_f32_e32 v59, v59
	s_nop 0
	v_pk_mul_f32 v[58:59], v[62:63], v[58:59]
	v_lshlrev_b32_e32 v62, 16, v210
	v_and_b32_e32 v63, 0xffff0000, v210
	v_pk_mul_f32 v[58:59], v[58:59], v[62:63]
	v_mul_f32_e32 v62, 0xbfb8aa3b, v61
	v_exp_f32_e32 v62, v62
	v_and_b32_e32 v63, 0xffff0000, v213
	v_cvt_pk_bf16_f32 v58, v58, v59
	v_cvt_pk_bf16_f32 v59, v64, v65
	v_add_f32_e32 v62, 1.0, v62
	v_rcp_f32_e32 v69, v62
	v_lshlrev_b32_e32 v62, 16, v213
	v_pk_mul_f32 v[60:61], v[60:61], v[68:69]
	s_nop 0
	v_pk_mul_f32 v[62:63], v[60:61], v[62:63]
	v_cvt_pk_bf16_f32 v60, v76, v77
	v_cvt_pk_bf16_f32 v61, v62, v63
	global_store_dwordx4 v[74:75], v[58:61], off
	s_nop 0
	s_nop 0
	v_mul_f32_e32 v59, 0xbfb8aa3b, v50
	v_exp_f32_e32 v59, v59
	v_mul_f32_e32 v58, 0xbfb8aa3b, v52
	v_exp_f32_e32 v58, v58
	v_add_f32_e32 v59, 1.0, v59
	v_rcp_f32_e32 v64, v59
	v_mul_f32_e32 v59, 0xbfb8aa3b, v51
	v_exp_f32_e32 v59, v59
	v_add_f32_e32 v58, 1.0, v58
	v_rcp_f32_e32 v58, v58
	v_add_f32_e32 v59, 1.0, v59
	v_rcp_f32_e32 v65, v59
	s_nop 0
	v_pk_mul_f32 v[50:51], v[50:51], v[64:65]
	v_lshlrev_b32_e32 v64, 16, v216
	v_and_b32_e32 v65, 0xffff0000, v216
	v_pk_mul_f32 v[64:65], v[50:51], v[64:65]
	v_mul_f32_e32 v50, 0xbfb8aa3b, v56
	v_mul_f32_e32 v51, 0xbfb8aa3b, v57
	v_exp_f32_e32 v50, v50
	v_exp_f32_e32 v51, v51
	v_add_f32_e32 v50, 1.0, v50
	v_add_f32_e32 v51, 1.0, v51
	v_rcp_f32_e32 v50, v50
	v_rcp_f32_e32 v51, v51
	s_nop 0
	v_pk_mul_f32 v[50:51], v[56:57], v[50:51]
	v_lshlrev_b32_e32 v56, 16, v215
	v_and_b32_e32 v57, 0xffff0000, v215
	v_pk_mul_f32 v[56:57], v[50:51], v[56:57]
	v_mul_f32_e32 v50, 0xbfb8aa3b, v54
	v_mul_f32_e32 v51, 0xbfb8aa3b, v55
	v_exp_f32_e32 v50, v50
	v_exp_f32_e32 v51, v51
	v_add_f32_e32 v50, 1.0, v50
	v_add_f32_e32 v51, 1.0, v51
	v_rcp_f32_e32 v50, v50
	v_rcp_f32_e32 v51, v51
	s_nop 0
	v_pk_mul_f32 v[50:51], v[54:55], v[50:51]
	v_lshlrev_b32_e32 v54, 16, v214
	v_and_b32_e32 v55, 0xffff0000, v214
	v_pk_mul_f32 v[50:51], v[50:51], v[54:55]
	v_mul_f32_e32 v54, 0xbfb8aa3b, v53
	v_exp_f32_e32 v54, v54
	v_and_b32_e32 v55, 0xffff0000, v217
	v_cvt_pk_bf16_f32 v50, v50, v51
	v_cvt_pk_bf16_f32 v51, v56, v57
	v_add_f32_e32 v54, 1.0, v54
	v_rcp_f32_e32 v59, v54
	v_lshlrev_b32_e32 v54, 16, v217
	v_pk_mul_f32 v[52:53], v[52:53], v[58:59]
	v_add_co_u32_e32 v58, vcc, s13, v140
	v_pk_mul_f32 v[54:55], v[52:53], v[54:55]
	s_nop 0
	v_addc_co_u32_e32 v59, vcc, 0, v141, vcc
	v_cvt_pk_bf16_f32 v53, v54, v55
	s_nop 0
	v_cvt_pk_bf16_f32 v52, v64, v65
	global_store_dwordx4 v[66:67], v[50:53], off offset:256
	s_mov_b32 s13, 0xa0000
	s_nop 0
	v_mul_f32_e32 v53, 0xbfb8aa3b, v42
	v_exp_f32_e32 v53, v53
	v_mul_f32_e32 v50, 0xbfb8aa3b, v44
	v_exp_f32_e32 v50, v50
	v_add_f32_e32 v53, 1.0, v53
	v_rcp_f32_e32 v60, v53
	v_mul_f32_e32 v53, 0xbfb8aa3b, v43
; DI unsigned cvt_pk_bf16(float lo, float hi) { const f32x2_t v = {lo, hi}; const bf16v2_t b = __builtin_convertvector(v, bf16v2_t); return __builtin_bit_cast(unsigned, b); }
;     DI void operator()(const f32x4 (&acc)[2][2][4][2], const Unit& u, int wr, int wc, int fr, int fq) const {
;         const int row0 = u.pm * BM + wr * 64 + fr, col0 = u.pn * BM + wc * 32 + 8 * fq;
; #pragma unroll
;         for (int ai = 0; ai < 2; ++ai)
; #pragma unroll
;             for (int m = 0; m < 4; ++m)
; #pragma unroll
;                 for (int bj = 0; bj < 2; ++bj) f.store8(row0 + ai * HALF + m * 16, col0 + bj * HALF, acc[ai][bj][m][0], acc[ai][bj][m][1]);
;     DI void store8(int row, int col, f32x4 a, f32x4 b) const {
;         bf16_t* d = o + (size_t)row * 2048 + col;
;         const u32x4 ov = *(const u32x4*)d;
;         const unsigned ow[4] = {ov.x, ov.y, ov.z, ov.w}; float y[8];
; #pragma unroll
;         for (int i = 0; i < 8; ++i) { const float z = i < 4 ? a[i] : b[i - 4]; const float of = (i & 1) ? __uint_as_float(ow[i >> 1] & 0xffff0000u) : __uint_as_float(ow[i >> 1] << 16); y[i] = z * __builtin_amdgcn_rcpf(1.f + __expf(-z)) * of; }
;         u32x4 w; w.x = cvt_pk_bf16(y[0], y[1]); w.y = cvt_pk_bf16(y[2], y[3]); w.z = cvt_pk_bf16(y[4], y[5]); w.w = cvt_pk_bf16(y[6], y[7]); if (!dry) *(u32x4*)d = w;
	v_exp_f32_e32 v53, v53
	v_add_f32_e32 v50, 1.0, v50
	v_rcp_f32_e32 v52, v50
	v_lshl_add_u64 v[50:51], v[140:141], 0, s[20:21]
	v_add_f32_e32 v53, 1.0, v53
	v_rcp_f32_e32 v61, v53
	s_mov_b64 s[20:21], 0xa0000
	v_pk_mul_f32 v[42:43], v[42:43], v[60:61]
	v_lshlrev_b32_e32 v60, 16, v220
	v_and_b32_e32 v61, 0xffff0000, v220
	v_pk_mul_f32 v[60:61], v[42:43], v[60:61]
	v_mul_f32_e32 v42, 0xbfb8aa3b, v48
	v_mul_f32_e32 v43, 0xbfb8aa3b, v49
	v_exp_f32_e32 v42, v42
	v_exp_f32_e32 v43, v43
	v_add_f32_e32 v42, 1.0, v42
	v_add_f32_e32 v43, 1.0, v43
	v_rcp_f32_e32 v42, v42
	v_rcp_f32_e32 v43, v43
	s_nop 0
	v_pk_mul_f32 v[42:43], v[48:49], v[42:43]
	v_lshlrev_b32_e32 v48, 16, v219
	v_and_b32_e32 v49, 0xffff0000, v219
	v_pk_mul_f32 v[48:49], v[42:43], v[48:49]
	v_mul_f32_e32 v42, 0xbfb8aa3b, v46
	v_mul_f32_e32 v43, 0xbfb8aa3b, v47
	v_exp_f32_e32 v42, v42
	v_exp_f32_e32 v43, v43
	v_add_f32_e32 v42, 1.0, v42
	v_add_f32_e32 v43, 1.0, v43
	v_rcp_f32_e32 v42, v42
	v_rcp_f32_e32 v43, v43
	s_nop 0
	v_pk_mul_f32 v[42:43], v[46:47], v[42:43]
	v_lshlrev_b32_e32 v46, 16, v218
	v_and_b32_e32 v47, 0xffff0000, v218
	v_pk_mul_f32 v[42:43], v[42:43], v[46:47]
	v_mul_f32_e32 v46, 0xbfb8aa3b, v45
	v_exp_f32_e32 v46, v46
	v_and_b32_e32 v47, 0xffff0000, v221
	v_cvt_pk_bf16_f32 v42, v42, v43
	v_cvt_pk_bf16_f32 v43, v48, v49
	v_add_f32_e32 v46, 1.0, v46
	v_rcp_f32_e32 v53, v46
	v_lshlrev_b32_e32 v46, 16, v221
	v_pk_mul_f32 v[44:45], v[44:45], v[52:53]
	s_nop 0
	v_pk_mul_f32 v[46:47], v[44:45], v[46:47]
	v_cvt_pk_bf16_f32 v44, v60, v61
	v_cvt_pk_bf16_f32 v45, v46, v47
	global_store_dwordx4 v[58:59], v[42:45], off
	s_nop 0
	s_nop 0
	v_mul_f32_e32 v43, 0xbfb8aa3b, v34
	v_exp_f32_e32 v43, v43
	v_mul_f32_e32 v42, 0xbfb8aa3b, v36
	v_exp_f32_e32 v42, v42
	v_add_f32_e32 v43, 1.0, v43
	v_rcp_f32_e32 v48, v43
	v_mul_f32_e32 v43, 0xbfb8aa3b, v35
	v_exp_f32_e32 v43, v43
	v_add_f32_e32 v42, 1.0, v42
	v_rcp_f32_e32 v42, v42
	v_add_f32_e32 v43, 1.0, v43
	v_rcp_f32_e32 v49, v43
	s_nop 0
	v_pk_mul_f32 v[34:35], v[34:35], v[48:49]
	v_lshlrev_b32_e32 v48, 16, v224
	v_and_b32_e32 v49, 0xffff0000, v224
	v_pk_mul_f32 v[48:49], v[34:35], v[48:49]
	v_mul_f32_e32 v34, 0xbfb8aa3b, v40
	v_mul_f32_e32 v35, 0xbfb8aa3b, v41
	v_exp_f32_e32 v34, v34
	v_exp_f32_e32 v35, v35
	v_add_f32_e32 v34, 1.0, v34
	v_add_f32_e32 v35, 1.0, v35
	v_rcp_f32_e32 v34, v34
	v_rcp_f32_e32 v35, v35
	s_nop 0
	v_pk_mul_f32 v[34:35], v[40:41], v[34:35]
	v_lshlrev_b32_e32 v40, 16, v223
	v_and_b32_e32 v41, 0xffff0000, v223
	v_pk_mul_f32 v[40:41], v[34:35], v[40:41]
	v_mul_f32_e32 v34, 0xbfb8aa3b, v38
	v_mul_f32_e32 v35, 0xbfb8aa3b, v39
	v_exp_f32_e32 v34, v34
	v_exp_f32_e32 v35, v35
	v_add_f32_e32 v34, 1.0, v34
	v_add_f32_e32 v35, 1.0, v35
	v_rcp_f32_e32 v34, v34
	v_rcp_f32_e32 v35, v35
	s_nop 0
	v_pk_mul_f32 v[34:35], v[38:39], v[34:35]
	v_lshlrev_b32_e32 v38, 16, v222
	v_and_b32_e32 v39, 0xffff0000, v222
	v_pk_mul_f32 v[34:35], v[34:35], v[38:39]
	v_mul_f32_e32 v38, 0xbfb8aa3b, v37
	v_exp_f32_e32 v38, v38
	v_and_b32_e32 v39, 0xffff0000, v225
	v_cvt_pk_bf16_f32 v34, v34, v35
	v_cvt_pk_bf16_f32 v35, v40, v41
	v_add_f32_e32 v38, 1.0, v38
	v_rcp_f32_e32 v43, v38
	v_lshlrev_b32_e32 v38, 16, v225
	v_pk_mul_f32 v[36:37], v[36:37], v[42:43]
	v_add_co_u32_e32 v42, vcc, s13, v140
	v_pk_mul_f32 v[38:39], v[36:37], v[38:39]
	s_nop 0
	v_addc_co_u32_e32 v43, vcc, 0, v141, vcc
	v_cvt_pk_bf16_f32 v37, v38, v39
	s_nop 0
	v_cvt_pk_bf16_f32 v36, v48, v49
	global_store_dwordx4 v[50:51], v[34:37], off offset:256
	s_mov_b32 s13, 0xb0000
	s_nop 0
	v_mul_f32_e32 v37, 0xbfb8aa3b, v26
	v_exp_f32_e32 v37, v37
	v_mul_f32_e32 v34, 0xbfb8aa3b, v28
	v_exp_f32_e32 v34, v34
	v_add_f32_e32 v37, 1.0, v37
	v_rcp_f32_e32 v44, v37
	v_mul_f32_e32 v37, 0xbfb8aa3b, v27
	v_exp_f32_e32 v37, v37
	v_add_f32_e32 v34, 1.0, v34
	v_rcp_f32_e32 v36, v34
	v_lshl_add_u64 v[34:35], v[140:141], 0, s[20:21]
	v_add_f32_e32 v37, 1.0, v37
	v_rcp_f32_e32 v45, v37
	s_mov_b64 s[20:21], 0xb0000
	v_pk_mul_f32 v[26:27], v[26:27], v[44:45]
	v_lshlrev_b32_e32 v44, 16, v228
	v_and_b32_e32 v45, 0xffff0000, v228
	v_pk_mul_f32 v[44:45], v[26:27], v[44:45]
	v_mul_f32_e32 v26, 0xbfb8aa3b, v32
	v_mul_f32_e32 v27, 0xbfb8aa3b, v33
	v_exp_f32_e32 v26, v26
	v_exp_f32_e32 v27, v27
	v_add_f32_e32 v26, 1.0, v26
	v_add_f32_e32 v27, 1.0, v27
	v_rcp_f32_e32 v26, v26
	v_rcp_f32_e32 v27, v27
	s_nop 0
	v_pk_mul_f32 v[26:27], v[32:33], v[26:27]
	v_lshlrev_b32_e32 v32, 16, v227
	v_and_b32_e32 v33, 0xffff0000, v227
	v_pk_mul_f32 v[32:33], v[26:27], v[32:33]
	v_mul_f32_e32 v26, 0xbfb8aa3b, v30
	v_mul_f32_e32 v27, 0xbfb8aa3b, v31
	v_exp_f32_e32 v26, v26
	v_exp_f32_e32 v27, v27
	v_add_f32_e32 v26, 1.0, v26
	v_add_f32_e32 v27, 1.0, v27
	v_rcp_f32_e32 v26, v26
	v_rcp_f32_e32 v27, v27
	s_nop 0
	v_pk_mul_f32 v[26:27], v[30:31], v[26:27]
	v_lshlrev_b32_e32 v30, 16, v226
	v_and_b32_e32 v31, 0xffff0000, v226
	v_pk_mul_f32 v[26:27], v[26:27], v[30:31]
	v_mul_f32_e32 v30, 0xbfb8aa3b, v29
	v_exp_f32_e32 v30, v30
	v_and_b32_e32 v31, 0xffff0000, v229
	v_cvt_pk_bf16_f32 v26, v26, v27
	v_cvt_pk_bf16_f32 v27, v32, v33
	v_add_f32_e32 v30, 1.0, v30
	v_rcp_f32_e32 v37, v30
	v_lshlrev_b32_e32 v30, 16, v229
	v_pk_mul_f32 v[28:29], v[28:29], v[36:37]
	s_nop 0
	v_pk_mul_f32 v[30:31], v[28:29], v[30:31]
	v_cvt_pk_bf16_f32 v28, v44, v45
	v_cvt_pk_bf16_f32 v29, v30, v31
	global_store_dwordx4 v[42:43], v[26:29], off
	s_nop 0
	s_nop 0
	v_mul_f32_e32 v27, 0xbfb8aa3b, v18
	v_exp_f32_e32 v27, v27
	v_mul_f32_e32 v26, 0xbfb8aa3b, v20
; DI unsigned cvt_pk_bf16(float lo, float hi) { const f32x2_t v = {lo, hi}; const bf16v2_t b = __builtin_convertvector(v, bf16v2_t); return __builtin_bit_cast(unsigned, b); }
;     DI void operator()(const f32x4 (&acc)[2][2][4][2], const Unit& u, int wr, int wc, int fr, int fq) const {
;         const int row0 = u.pm * BM + wr * 64 + fr, col0 = u.pn * BM + wc * 32 + 8 * fq;
; #pragma unroll
;         for (int ai = 0; ai < 2; ++ai)
; #pragma unroll
;             for (int m = 0; m < 4; ++m)
; #pragma unroll
;                 for (int bj = 0; bj < 2; ++bj) f.store8(row0 + ai * HALF + m * 16, col0 + bj * HALF, acc[ai][bj][m][0], acc[ai][bj][m][1]);
;     DI void store8(int row, int col, f32x4 a, f32x4 b) const {
;         bf16_t* d = o + (size_t)row * 2048 + col;
;         const u32x4 ov = *(const u32x4*)d;
;         const unsigned ow[4] = {ov.x, ov.y, ov.z, ov.w}; float y[8];
; #pragma unroll
;         for (int i = 0; i < 8; ++i) { const float z = i < 4 ? a[i] : b[i - 4]; const float of = (i & 1) ? __uint_as_float(ow[i >> 1] & 0xffff0000u) : __uint_as_float(ow[i >> 1] << 16); y[i] = z * __builtin_amdgcn_rcpf(1.f + __expf(-z)) * of; }
;         u32x4 w; w.x = cvt_pk_bf16(y[0], y[1]); w.y = cvt_pk_bf16(y[2], y[3]); w.z = cvt_pk_bf16(y[4], y[5]); w.w = cvt_pk_bf16(y[6], y[7]); if (!dry) *(u32x4*)d = w;
	v_exp_f32_e32 v26, v26
	v_add_f32_e32 v27, 1.0, v27
	v_rcp_f32_e32 v32, v27
	v_mul_f32_e32 v27, 0xbfb8aa3b, v19
	v_exp_f32_e32 v27, v27
	v_add_f32_e32 v26, 1.0, v26
	v_rcp_f32_e32 v26, v26
	v_add_f32_e32 v27, 1.0, v27
	v_rcp_f32_e32 v33, v27
	s_nop 0
	v_pk_mul_f32 v[18:19], v[18:19], v[32:33]
	v_lshlrev_b32_e32 v32, 16, v250
	v_and_b32_e32 v33, 0xffff0000, v250
	v_pk_mul_f32 v[32:33], v[18:19], v[32:33]
	v_mul_f32_e32 v18, 0xbfb8aa3b, v24
	v_mul_f32_e32 v19, 0xbfb8aa3b, v25
	v_exp_f32_e32 v18, v18
	v_exp_f32_e32 v19, v19
	v_add_f32_e32 v18, 1.0, v18
	v_add_f32_e32 v19, 1.0, v19
	v_rcp_f32_e32 v18, v18
	v_rcp_f32_e32 v19, v19
	s_nop 0
	v_pk_mul_f32 v[18:19], v[24:25], v[18:19]
	v_lshlrev_b32_e32 v24, 16, v249
	v_and_b32_e32 v25, 0xffff0000, v249
	v_pk_mul_f32 v[24:25], v[18:19], v[24:25]
	v_mul_f32_e32 v18, 0xbfb8aa3b, v22
	v_mul_f32_e32 v19, 0xbfb8aa3b, v23
	v_exp_f32_e32 v18, v18
	v_exp_f32_e32 v19, v19
	v_add_f32_e32 v18, 1.0, v18
	v_add_f32_e32 v19, 1.0, v19
	v_rcp_f32_e32 v18, v18
	v_rcp_f32_e32 v19, v19
	s_nop 0
	v_pk_mul_f32 v[18:19], v[22:23], v[18:19]
	v_lshlrev_b32_e32 v22, 16, v248
	v_and_b32_e32 v23, 0xffff0000, v248
	v_pk_mul_f32 v[18:19], v[18:19], v[22:23]
	v_mul_f32_e32 v22, 0xbfb8aa3b, v21
	v_exp_f32_e32 v22, v22
	v_and_b32_e32 v23, 0xffff0000, v251
	v_cvt_pk_bf16_f32 v18, v18, v19
	v_cvt_pk_bf16_f32 v19, v24, v25
	v_add_f32_e32 v22, 1.0, v22
	v_rcp_f32_e32 v27, v22
	v_lshlrev_b32_e32 v22, 16, v251
	v_pk_mul_f32 v[20:21], v[20:21], v[26:27]
	v_add_co_u32_e32 v26, vcc, s13, v140
	v_pk_mul_f32 v[22:23], v[20:21], v[22:23]
	s_nop 0
	v_addc_co_u32_e32 v27, vcc, 0, v141, vcc
	v_cvt_pk_bf16_f32 v21, v22, v23
	s_nop 0
	v_cvt_pk_bf16_f32 v20, v32, v33
	global_store_dwordx4 v[34:35], v[18:21], off offset:256
	s_andn2_b64 vcc, exec, s[38:39]
	s_nop 0
	v_mul_f32_e32 v21, 0xbfb8aa3b, v10
	v_exp_f32_e32 v21, v21
	v_mul_f32_e32 v18, 0xbfb8aa3b, v12
	v_exp_f32_e32 v18, v18
	v_add_f32_e32 v21, 1.0, v21
	v_rcp_f32_e32 v28, v21
	v_mul_f32_e32 v21, 0xbfb8aa3b, v11
	v_exp_f32_e32 v21, v21
	v_add_f32_e32 v18, 1.0, v18
	v_rcp_f32_e32 v20, v18
	v_lshl_add_u64 v[18:19], v[140:141], 0, s[20:21]
	v_add_f32_e32 v21, 1.0, v21
	v_rcp_f32_e32 v29, v21
	s_mov_b64 s[20:21], -1
	v_pk_mul_f32 v[10:11], v[10:11], v[28:29]
	v_lshlrev_b32_e32 v28, 16, v254
	v_and_b32_e32 v29, 0xffff0000, v254
	v_pk_mul_f32 v[28:29], v[10:11], v[28:29]
	v_mul_f32_e32 v10, 0xbfb8aa3b, v16
	v_mul_f32_e32 v11, 0xbfb8aa3b, v17
	v_exp_f32_e32 v10, v10
	v_exp_f32_e32 v11, v11
	v_add_f32_e32 v10, 1.0, v10
	v_add_f32_e32 v11, 1.0, v11
	v_rcp_f32_e32 v10, v10
	v_rcp_f32_e32 v11, v11
	s_nop 0
	v_pk_mul_f32 v[10:11], v[16:17], v[10:11]
	v_lshlrev_b32_e32 v16, 16, v253
	v_and_b32_e32 v17, 0xffff0000, v253
	v_pk_mul_f32 v[16:17], v[10:11], v[16:17]
	v_mul_f32_e32 v10, 0xbfb8aa3b, v14
	v_mul_f32_e32 v11, 0xbfb8aa3b, v15
	v_exp_f32_e32 v10, v10
	v_exp_f32_e32 v11, v11
	v_add_f32_e32 v10, 1.0, v10
	v_add_f32_e32 v11, 1.0, v11
	v_rcp_f32_e32 v10, v10
	v_rcp_f32_e32 v11, v11
	s_nop 0
	v_pk_mul_f32 v[10:11], v[14:15], v[10:11]
	v_lshlrev_b32_e32 v14, 16, v252
	v_and_b32_e32 v15, 0xffff0000, v252
	v_pk_mul_f32 v[10:11], v[10:11], v[14:15]
	v_mul_f32_e32 v14, 0xbfb8aa3b, v13
	v_exp_f32_e32 v14, v14
	v_and_b32_e32 v15, 0xffff0000, v255
	v_cvt_pk_bf16_f32 v10, v10, v11
	v_cvt_pk_bf16_f32 v11, v16, v17
	v_add_f32_e32 v14, 1.0, v14
	v_rcp_f32_e32 v21, v14
	v_lshlrev_b32_e32 v14, 16, v255
	v_pk_mul_f32 v[12:13], v[12:13], v[20:21]
	s_nop 0
	v_pk_mul_f32 v[14:15], v[12:13], v[14:15]
	v_cvt_pk_bf16_f32 v12, v28, v29
	v_cvt_pk_bf16_f32 v13, v14, v15
	global_store_dwordx4 v[26:27], v[10:13], off
	v_mul_f32_e32 v15, 0xbfb8aa3b, v2
	v_exp_f32_e32 v15, v15
	v_mul_f32_e32 v10, 0xbfb8aa3b, v4
	v_exp_f32_e32 v10, v10
	v_add_f32_e32 v15, 1.0, v15
	v_rcp_f32_e32 v16, v15
	v_add_f32_e32 v10, 1.0, v10
	v_rcp_f32_e32 v14, v10
	global_load_dwordx4 v[10:13], v[18:19], off offset:256
	v_mul_f32_e32 v15, 0xbfb8aa3b, v3
	v_exp_f32_e32 v15, v15
	s_nop 0
	v_add_f32_e32 v15, 1.0, v15
	v_rcp_f32_e32 v17, v15
	s_nop 0
	v_pk_mul_f32 v[2:3], v[2:3], v[16:17]
	s_waitcnt vmcnt(0)
	v_lshlrev_b32_e32 v16, 16, v12
	v_and_b32_e32 v17, 0xffff0000, v12
	v_pk_mul_f32 v[16:17], v[2:3], v[16:17]
	v_mul_f32_e32 v2, 0xbfb8aa3b, v8
	v_mul_f32_e32 v3, 0xbfb8aa3b, v9
	v_exp_f32_e32 v2, v2
	v_exp_f32_e32 v3, v3
	v_add_f32_e32 v2, 1.0, v2
	v_add_f32_e32 v3, 1.0, v3
	v_rcp_f32_e32 v2, v2
	v_rcp_f32_e32 v3, v3
	s_nop 0
	v_pk_mul_f32 v[2:3], v[8:9], v[2:3]
	v_lshlrev_b32_e32 v8, 16, v11
	v_and_b32_e32 v9, 0xffff0000, v11
	v_pk_mul_f32 v[8:9], v[2:3], v[8:9]
	v_mul_f32_e32 v2, 0xbfb8aa3b, v6
	v_mul_f32_e32 v3, 0xbfb8aa3b, v7
	v_exp_f32_e32 v2, v2
	v_exp_f32_e32 v3, v3
	v_add_f32_e32 v2, 1.0, v2
	v_add_f32_e32 v3, 1.0, v3
	v_rcp_f32_e32 v2, v2
	v_rcp_f32_e32 v3, v3
	s_nop 0
	v_pk_mul_f32 v[2:3], v[6:7], v[2:3]
	v_lshlrev_b32_e32 v6, 16, v10
	v_and_b32_e32 v7, 0xffff0000, v10
	v_pk_mul_f32 v[2:3], v[2:3], v[6:7]
	v_mul_f32_e32 v6, 0xbfb8aa3b, v5
	v_exp_f32_e32 v6, v6
	v_and_b32_e32 v7, 0xffff0000, v13
	v_cvt_pk_bf16_f32 v2, v2, v3
	v_cvt_pk_bf16_f32 v3, v8, v9
	v_add_f32_e32 v6, 1.0, v6
	v_rcp_f32_e32 v15, v6
	v_lshlrev_b32_e32 v6, 16, v13
	v_pk_mul_f32 v[4:5], v[4:5], v[14:15]
	s_nop 0
	v_pk_mul_f32 v[6:7], v[4:5], v[6:7]
	v_cvt_pk_bf16_f32 v4, v16, v17
	v_cvt_pk_bf16_f32 v5, v6, v7
	global_store_dwordx4 v[18:19], v[2:5], off offset:256
	s_cbranch_vccnz .LBB0_50
	s_andn2_b64 vcc, exec, s[8:9]
	s_cbranch_vccnz .LBB0_49
	s_barrier
	s_branch .LBB0_49
